# attention mask-free steps hand-scheduled: second-half QK MFMAs inside the first softmax (own accumulator block), V reads under the second softmax; + stagger + h2lds + aligned loops
# speedup vs baseline: 1.0110x; 1.0060x over previous
.LBB0_115:
	s_lshl_b64 s[4:5], s[42:43], 13
	s_add_u32 s4, s50, s4
	s_addc_u32 s5, s51, s5
	s_lshl_b64 s[8:9], s[42:43], 14
	s_add_u32 s8, s52, s8
	v_lshl_add_u64 v[252:253], s[4:5], 0, v[176:177]
	s_addc_u32 s9, s53, s9
	global_load_dwordx4 v[160:163], v[252:253], off
	v_add_co_u32_e32 v252, vcc, 0x100000, v252
	v_lshl_add_u64 v[254:255], s[8:9], 0, v[176:177]
	s_nop 0
	v_addc_co_u32_e32 v253, vcc, 0, v253, vcc
	global_load_dwordx4 v[168:171], v[252:253], off
	v_add_co_u32_e32 v252, vcc, 0x2000, v254
	global_load_dwordx4 v[164:167], v[254:255], off
	s_nop 0
	v_addc_co_u32_e32 v253, vcc, 0, v255, vcc
	global_load_dwordx4 v[172:175], v[252:253], off

.Lnd_107:
	s_and_b32 s33, s42, 1
	s_mul_i32 s6, s33, 0x9000
	v_add_u32_e32 v199, s6, v187
	v_add_u32_e32 v198, s6, v188
	s_mov_b64 s[54:55], exec
	v_readfirstlane_b32 s4, v186
	s_bitcmp1_b32 s4, 8
	s_cbranch_scc1 .Lab_B
	ds_read_b128 v[216:219], v199 offset:0
	ds_read_b128 v[232:235], v193 offset:0
	ds_read_b128 v[220:223], v199 offset:32
	ds_read_b128 v[236:239], v193 offset:32
	ds_read_b128 v[224:227], v199 offset:64
	ds_read_b128 v[244:247], v193 offset:64
	ds_read_b128 v[228:231], v199 offset:96
	ds_read_b128 v[248:251], v193 offset:96
	s_waitcnt lgkmcnt(6)
	v_mfma_f32_32x32x16_bf16 v[144:159], v[216:219], v[232:235], v[0:15]
	s_waitcnt lgkmcnt(4)
	v_mfma_f32_32x32x16_bf16 v[144:159], v[220:223], v[236:239], v[144:159]
	s_waitcnt lgkmcnt(2)
	v_mfma_f32_32x32x16_bf16 v[144:159], v[224:227], v[244:247], v[144:159]
	s_waitcnt lgkmcnt(0)
	v_mfma_f32_32x32x16_bf16 v[144:159], v[228:231], v[248:251], v[144:159]
	ds_read_b128 v[216:219], v199 offset:9216
	ds_read_b128 v[232:235], v193 offset:36864
	ds_read_b128 v[220:223], v199 offset:9248
	ds_read_b128 v[236:239], v193 offset:36896
	ds_read_b128 v[224:227], v199 offset:9280
	ds_read_b128 v[244:247], v193 offset:36928
	ds_read_b128 v[228:231], v199 offset:9312
	ds_read_b128 v[248:251], v193 offset:36960
	s_nop 3
	v_exp_f32_e32 v144, v144
	v_exp_f32_e32 v145, v145
	v_exp_f32_e32 v146, v146
	v_exp_f32_e32 v147, v147
	v_exp_f32_e32 v148, v148
	v_exp_f32_e32 v149, v149
	v_exp_f32_e32 v150, v150
	v_exp_f32_e32 v151, v151
	v_exp_f32_e32 v152, v152
	v_exp_f32_e32 v153, v153
	v_exp_f32_e32 v154, v154
	v_exp_f32_e32 v155, v155
	v_exp_f32_e32 v156, v156
	v_exp_f32_e32 v157, v157
	v_exp_f32_e32 v158, v158
	v_exp_f32_e32 v159, v159
	v_add_f32_e32 v243, v144, v145
	v_add_f32_e32 v243, v146, v243
	v_add_f32_e32 v243, v147, v243
	v_add_f32_e32 v243, v148, v243
	v_add_f32_e32 v243, v149, v243
	v_add_f32_e32 v243, v150, v243
	v_add_f32_e32 v243, v151, v243
	s_waitcnt lgkmcnt(6)
	v_mfma_f32_32x32x16_bf16 v[200:215], v[216:219], v[232:235], v[0:15]
	s_waitcnt lgkmcnt(4)
	v_mfma_f32_32x32x16_bf16 v[200:215], v[220:223], v[236:239], v[200:215]
	s_waitcnt lgkmcnt(2)
	v_mfma_f32_32x32x16_bf16 v[200:215], v[224:227], v[244:247], v[200:215]
	s_waitcnt lgkmcnt(0)
	v_mfma_f32_32x32x16_bf16 v[200:215], v[228:231], v[248:251], v[200:215]
	v_add_f32_e32 v243, v152, v243
	v_add_f32_e32 v243, v153, v243
	v_add_f32_e32 v243, v154, v243
	v_add_f32_e32 v243, v155, v243
	v_add_f32_e32 v243, v156, v243
	v_add_f32_e32 v243, v157, v243
	v_add_f32_e32 v243, v158, v243
	v_add_f32_e32 v243, v159, v243
	v_add_f32_e32 v196, v196, v243
	v_cvt_pk_bf16_f32 v144, v144, v145
	v_cvt_pk_bf16_f32 v145, v146, v147
	v_cvt_pk_bf16_f32 v146, v148, v149
	v_cvt_pk_bf16_f32 v147, v150, v151
	v_cvt_pk_bf16_f32 v148, v152, v153
	v_cvt_pk_bf16_f32 v149, v154, v155
	v_cvt_pk_bf16_f32 v150, v156, v157
	v_cvt_pk_bf16_f32 v151, v158, v159
	ds_read_b128 v[216:219], v198 offset:0
	ds_read_b128 v[220:223], v198 offset:32
	ds_read_b128 v[224:227], v198 offset:4608
	ds_read_b128 v[228:231], v198 offset:4640
	ds_read_b128 v[232:235], v198 offset:9216
	ds_read_b128 v[236:239], v198 offset:9248
	ds_read_b128 v[244:247], v198 offset:13824
	ds_read_b128 v[248:251], v198 offset:13856
	v_exp_f32_e32 v200, v200
	v_exp_f32_e32 v201, v201
	v_exp_f32_e32 v202, v202
	v_exp_f32_e32 v203, v203
	v_exp_f32_e32 v204, v204
	v_exp_f32_e32 v205, v205
	v_exp_f32_e32 v206, v206
	v_exp_f32_e32 v207, v207
	v_exp_f32_e32 v208, v208
	v_exp_f32_e32 v209, v209
	v_exp_f32_e32 v210, v210
	v_exp_f32_e32 v211, v211
	v_exp_f32_e32 v212, v212
	v_exp_f32_e32 v213, v213
	v_exp_f32_e32 v214, v214
	v_exp_f32_e32 v215, v215
	v_add_f32_e32 v243, v200, v201
	v_add_f32_e32 v243, v202, v243
	v_add_f32_e32 v243, v203, v243
	v_add_f32_e32 v243, v204, v243
	v_add_f32_e32 v243, v205, v243
	v_add_f32_e32 v243, v206, v243
	v_add_f32_e32 v243, v207, v243
	v_add_f32_e32 v243, v208, v243
	v_add_f32_e32 v243, v209, v243
	v_add_f32_e32 v243, v210, v243
	v_add_f32_e32 v243, v211, v243
	v_add_f32_e32 v243, v212, v243
	v_add_f32_e32 v243, v213, v243
	v_add_f32_e32 v243, v214, v243
	v_add_f32_e32 v243, v215, v243
	v_add_f32_e32 v197, v197, v243
	v_cvt_pk_bf16_f32 v200, v200, v201
	v_cvt_pk_bf16_f32 v201, v202, v203
	v_cvt_pk_bf16_f32 v202, v204, v205
	v_cvt_pk_bf16_f32 v203, v206, v207
	v_cvt_pk_bf16_f32 v204, v208, v209
	v_cvt_pk_bf16_f32 v205, v210, v211
	v_cvt_pk_bf16_f32 v206, v212, v213
	v_cvt_pk_bf16_f32 v207, v214, v215
	s_waitcnt lgkmcnt(7)
	v_mfma_f32_32x32x16_bf16 v[112:127], v[216:219], v[144:147], v[112:127]
	v_mfma_f32_32x32x16_bf16 v[128:143], v[216:219], v[200:203], v[128:143]
	s_waitcnt lgkmcnt(5)
	v_mfma_f32_32x32x16_bf16 v[80:95], v[224:227], v[144:147], v[80:95]
	v_mfma_f32_32x32x16_bf16 v[96:111], v[224:227], v[200:203], v[96:111]
	s_waitcnt lgkmcnt(3)
	v_mfma_f32_32x32x16_bf16 v[48:63], v[232:235], v[144:147], v[48:63]
	v_mfma_f32_32x32x16_bf16 v[64:79], v[232:235], v[200:203], v[64:79]
	s_waitcnt lgkmcnt(1)
	v_mfma_f32_32x32x16_bf16 v[16:31], v[244:247], v[144:147], v[16:31]
	v_mfma_f32_32x32x16_bf16 v[32:47], v[244:247], v[200:203], v[32:47]
	s_waitcnt lgkmcnt(0)
	v_mfma_f32_32x32x16_bf16 v[112:127], v[220:223], v[148:151], v[112:127]
	v_mfma_f32_32x32x16_bf16 v[128:143], v[220:223], v[204:207], v[128:143]
	v_mfma_f32_32x32x16_bf16 v[80:95], v[228:231], v[148:151], v[80:95]
	v_mfma_f32_32x32x16_bf16 v[96:111], v[228:231], v[204:207], v[96:111]
	v_mfma_f32_32x32x16_bf16 v[48:63], v[236:239], v[148:151], v[48:63]
	v_mfma_f32_32x32x16_bf16 v[64:79], v[236:239], v[204:207], v[64:79]
	s_waitcnt lgkmcnt(0)
	v_mfma_f32_32x32x16_bf16 v[16:31], v[248:251], v[148:151], v[16:31]
	v_mfma_f32_32x32x16_bf16 v[32:47], v[248:251], v[204:207], v[32:47]
	ds_read_b128 v[216:219], v199 offset:4608
	ds_read_b128 v[232:235], v193 offset:0
	ds_read_b128 v[220:223], v199 offset:4640
	ds_read_b128 v[236:239], v193 offset:32
	ds_read_b128 v[224:227], v199 offset:4672
	ds_read_b128 v[244:247], v193 offset:64
	ds_read_b128 v[228:231], v199 offset:4704
	ds_read_b128 v[248:251], v193 offset:96
	s_waitcnt lgkmcnt(6)
	v_mfma_f32_32x32x16_bf16 v[144:159], v[216:219], v[232:235], v[0:15]
	s_waitcnt lgkmcnt(4)
	v_mfma_f32_32x32x16_bf16 v[144:159], v[220:223], v[236:239], v[144:159]
	s_waitcnt lgkmcnt(2)
	v_mfma_f32_32x32x16_bf16 v[144:159], v[224:227], v[244:247], v[144:159]
	s_waitcnt lgkmcnt(0)
	v_mfma_f32_32x32x16_bf16 v[144:159], v[228:231], v[248:251], v[144:159]
	ds_read_b128 v[216:219], v199 offset:13824
	ds_read_b128 v[232:235], v193 offset:36864
	ds_read_b128 v[220:223], v199 offset:13856
	ds_read_b128 v[236:239], v193 offset:36896
	ds_read_b128 v[224:227], v199 offset:13888
	ds_read_b128 v[244:247], v193 offset:36928
	ds_read_b128 v[228:231], v199 offset:13920
	ds_read_b128 v[248:251], v193 offset:36960
	s_nop 3
	v_exp_f32_e32 v144, v144
	v_exp_f32_e32 v145, v145
	v_exp_f32_e32 v146, v146
	v_exp_f32_e32 v147, v147
	v_exp_f32_e32 v148, v148
	v_exp_f32_e32 v149, v149
	v_exp_f32_e32 v150, v150
	v_exp_f32_e32 v151, v151
	v_exp_f32_e32 v152, v152
	v_exp_f32_e32 v153, v153
	v_exp_f32_e32 v154, v154
	v_exp_f32_e32 v155, v155
	v_exp_f32_e32 v156, v156
	v_exp_f32_e32 v157, v157
	v_exp_f32_e32 v158, v158
	v_exp_f32_e32 v159, v159
	v_add_f32_e32 v243, v144, v145
	v_add_f32_e32 v243, v146, v243
	v_add_f32_e32 v243, v147, v243
	v_add_f32_e32 v243, v148, v243
	v_add_f32_e32 v243, v149, v243
	v_add_f32_e32 v243, v150, v243
	v_add_f32_e32 v243, v151, v243
	s_waitcnt lgkmcnt(6)
	v_mfma_f32_32x32x16_bf16 v[200:215], v[216:219], v[232:235], v[0:15]
	s_waitcnt lgkmcnt(4)
	v_mfma_f32_32x32x16_bf16 v[200:215], v[220:223], v[236:239], v[200:215]
	s_waitcnt lgkmcnt(2)
	v_mfma_f32_32x32x16_bf16 v[200:215], v[224:227], v[244:247], v[200:215]
	s_waitcnt lgkmcnt(0)
	v_mfma_f32_32x32x16_bf16 v[200:215], v[228:231], v[248:251], v[200:215]
	v_add_f32_e32 v243, v152, v243
	v_add_f32_e32 v243, v153, v243
	v_add_f32_e32 v243, v154, v243
	v_add_f32_e32 v243, v155, v243
	v_add_f32_e32 v243, v156, v243
	v_add_f32_e32 v243, v157, v243
	v_add_f32_e32 v243, v158, v243
	v_add_f32_e32 v243, v159, v243
	v_add_f32_e32 v196, v196, v243
	v_cvt_pk_bf16_f32 v144, v144, v145
	v_cvt_pk_bf16_f32 v145, v146, v147
	v_cvt_pk_bf16_f32 v146, v148, v149
	v_cvt_pk_bf16_f32 v147, v150, v151
	v_cvt_pk_bf16_f32 v148, v152, v153
	v_cvt_pk_bf16_f32 v149, v154, v155
	v_cvt_pk_bf16_f32 v150, v156, v157
	v_cvt_pk_bf16_f32 v151, v158, v159
	ds_read_b128 v[216:219], v198 offset:64
	ds_read_b128 v[220:223], v198 offset:96
	ds_read_b128 v[224:227], v198 offset:4672
	ds_read_b128 v[228:231], v198 offset:4704
	ds_read_b128 v[232:235], v198 offset:9280
	ds_read_b128 v[236:239], v198 offset:9312
	ds_read_b128 v[244:247], v198 offset:13888
	ds_read_b128 v[248:251], v198 offset:13920
	v_exp_f32_e32 v200, v200
	v_exp_f32_e32 v201, v201
	v_exp_f32_e32 v202, v202
	v_exp_f32_e32 v203, v203
	v_exp_f32_e32 v204, v204
	v_exp_f32_e32 v205, v205
	v_exp_f32_e32 v206, v206
	v_exp_f32_e32 v207, v207
	v_exp_f32_e32 v208, v208
	v_exp_f32_e32 v209, v209
	v_exp_f32_e32 v210, v210
	v_exp_f32_e32 v211, v211
	v_exp_f32_e32 v212, v212
	v_exp_f32_e32 v213, v213
	v_exp_f32_e32 v214, v214
	v_exp_f32_e32 v215, v215
	v_add_f32_e32 v243, v200, v201
	v_add_f32_e32 v243, v202, v243
	v_add_f32_e32 v243, v203, v243
	v_add_f32_e32 v243, v204, v243
	v_add_f32_e32 v243, v205, v243
	v_add_f32_e32 v243, v206, v243
	v_add_f32_e32 v243, v207, v243
	v_add_f32_e32 v243, v208, v243
	v_add_f32_e32 v243, v209, v243
	v_add_f32_e32 v243, v210, v243
	v_add_f32_e32 v243, v211, v243
	v_add_f32_e32 v243, v212, v243
	v_add_f32_e32 v243, v213, v243
	v_add_f32_e32 v243, v214, v243
	v_add_f32_e32 v243, v215, v243
	v_add_f32_e32 v197, v197, v243
	v_cvt_pk_bf16_f32 v200, v200, v201
	v_cvt_pk_bf16_f32 v201, v202, v203
	v_cvt_pk_bf16_f32 v202, v204, v205
	v_cvt_pk_bf16_f32 v203, v206, v207
	v_cvt_pk_bf16_f32 v204, v208, v209
	v_cvt_pk_bf16_f32 v205, v210, v211
	v_cvt_pk_bf16_f32 v206, v212, v213
	v_cvt_pk_bf16_f32 v207, v214, v215
	s_waitcnt lgkmcnt(7)
	v_mfma_f32_32x32x16_bf16 v[112:127], v[216:219], v[144:147], v[112:127]
	v_mfma_f32_32x32x16_bf16 v[128:143], v[216:219], v[200:203], v[128:143]
	s_waitcnt lgkmcnt(5)
	v_mfma_f32_32x32x16_bf16 v[80:95], v[224:227], v[144:147], v[80:95]
	v_mfma_f32_32x32x16_bf16 v[96:111], v[224:227], v[200:203], v[96:111]
	s_waitcnt lgkmcnt(3)
	v_mfma_f32_32x32x16_bf16 v[48:63], v[232:235], v[144:147], v[48:63]
	v_mfma_f32_32x32x16_bf16 v[64:79], v[232:235], v[200:203], v[64:79]
	s_waitcnt lgkmcnt(1)
	v_mfma_f32_32x32x16_bf16 v[16:31], v[244:247], v[144:147], v[16:31]
	v_mfma_f32_32x32x16_bf16 v[32:47], v[244:247], v[200:203], v[32:47]
	s_waitcnt lgkmcnt(0)
	v_mfma_f32_32x32x16_bf16 v[112:127], v[220:223], v[148:151], v[112:127]
	v_mfma_f32_32x32x16_bf16 v[128:143], v[220:223], v[204:207], v[128:143]
	v_mfma_f32_32x32x16_bf16 v[80:95], v[228:231], v[148:151], v[80:95]
	v_mfma_f32_32x32x16_bf16 v[96:111], v[228:231], v[204:207], v[96:111]
	v_mfma_f32_32x32x16_bf16 v[48:63], v[236:239], v[148:151], v[48:63]
	v_mfma_f32_32x32x16_bf16 v[64:79], v[236:239], v[204:207], v[64:79]
	s_waitcnt lgkmcnt(0)
	v_mfma_f32_32x32x16_bf16 v[16:31], v[248:251], v[148:151], v[16:31]
	v_mfma_f32_32x32x16_bf16 v[32:47], v[248:251], v[204:207], v[32:47]
	s_branch .LBB0_111
.Lab_B:
	s_cmp_eq_u32 s42, 0
	s_cbranch_scc1 .Lab_B0
	v_mfma_f32_32x32x16_bf16 v[112:127], v[216:219], v[144:147], v[112:127]
	v_mfma_f32_32x32x16_bf16 v[128:143], v[216:219], v[200:203], v[128:143]
	v_mfma_f32_32x32x16_bf16 v[80:95], v[224:227], v[144:147], v[80:95]
	v_mfma_f32_32x32x16_bf16 v[96:111], v[224:227], v[200:203], v[96:111]
	v_mfma_f32_32x32x16_bf16 v[48:63], v[232:235], v[144:147], v[48:63]
	v_mfma_f32_32x32x16_bf16 v[64:79], v[232:235], v[200:203], v[64:79]
	v_mfma_f32_32x32x16_bf16 v[16:31], v[244:247], v[144:147], v[16:31]
	v_mfma_f32_32x32x16_bf16 v[32:47], v[244:247], v[200:203], v[32:47]
	v_mfma_f32_32x32x16_bf16 v[112:127], v[220:223], v[148:151], v[112:127]
	v_mfma_f32_32x32x16_bf16 v[128:143], v[220:223], v[204:207], v[128:143]
	v_mfma_f32_32x32x16_bf16 v[80:95], v[228:231], v[148:151], v[80:95]
	v_mfma_f32_32x32x16_bf16 v[96:111], v[228:231], v[204:207], v[96:111]
	v_mfma_f32_32x32x16_bf16 v[48:63], v[236:239], v[148:151], v[48:63]
	v_mfma_f32_32x32x16_bf16 v[64:79], v[236:239], v[204:207], v[64:79]
	v_mfma_f32_32x32x16_bf16 v[16:31], v[248:251], v[148:151], v[16:31]
	v_mfma_f32_32x32x16_bf16 v[32:47], v[248:251], v[204:207], v[32:47]
.Lab_B0:
	ds_read_b128 v[216:219], v199 offset:0
	ds_read_b128 v[232:235], v193 offset:0
	ds_read_b128 v[220:223], v199 offset:32
	ds_read_b128 v[236:239], v193 offset:32
	ds_read_b128 v[224:227], v199 offset:64
	ds_read_b128 v[244:247], v193 offset:64
	ds_read_b128 v[228:231], v199 offset:96
	ds_read_b128 v[248:251], v193 offset:96
	s_waitcnt lgkmcnt(6)
	v_mfma_f32_32x32x16_bf16 v[144:159], v[216:219], v[232:235], v[0:15]
	s_waitcnt lgkmcnt(4)
	v_mfma_f32_32x32x16_bf16 v[144:159], v[220:223], v[236:239], v[144:159]
	s_waitcnt lgkmcnt(2)
	v_mfma_f32_32x32x16_bf16 v[144:159], v[224:227], v[244:247], v[144:159]
	s_waitcnt lgkmcnt(0)
	v_mfma_f32_32x32x16_bf16 v[144:159], v[228:231], v[248:251], v[144:159]
	ds_read_b128 v[216:219], v199 offset:9216
	ds_read_b128 v[232:235], v193 offset:36864
	ds_read_b128 v[220:223], v199 offset:9248
	ds_read_b128 v[236:239], v193 offset:36896
	ds_read_b128 v[224:227], v199 offset:9280
	ds_read_b128 v[244:247], v193 offset:36928
	ds_read_b128 v[228:231], v199 offset:9312
	ds_read_b128 v[248:251], v193 offset:36960
	s_nop 3
	v_exp_f32_e32 v144, v144
	v_exp_f32_e32 v145, v145
	v_exp_f32_e32 v146, v146
	v_exp_f32_e32 v147, v147
	v_exp_f32_e32 v148, v148
	v_exp_f32_e32 v149, v149
	v_exp_f32_e32 v150, v150
	v_exp_f32_e32 v151, v151
	v_exp_f32_e32 v152, v152
	v_exp_f32_e32 v153, v153
	v_exp_f32_e32 v154, v154
	v_exp_f32_e32 v155, v155
	v_exp_f32_e32 v156, v156
	v_exp_f32_e32 v157, v157
	v_exp_f32_e32 v158, v158
	v_exp_f32_e32 v159, v159
	v_add_f32_e32 v243, v144, v145
	v_add_f32_e32 v243, v146, v243
	v_add_f32_e32 v243, v147, v243
	v_add_f32_e32 v243, v148, v243
	v_add_f32_e32 v243, v149, v243
	v_add_f32_e32 v243, v150, v243
	v_add_f32_e32 v243, v151, v243
	s_waitcnt lgkmcnt(6)
	v_mfma_f32_32x32x16_bf16 v[200:215], v[216:219], v[232:235], v[0:15]
	s_waitcnt lgkmcnt(4)
	v_mfma_f32_32x32x16_bf16 v[200:215], v[220:223], v[236:239], v[200:215]
	s_waitcnt lgkmcnt(2)
	v_mfma_f32_32x32x16_bf16 v[200:215], v[224:227], v[244:247], v[200:215]
	s_waitcnt lgkmcnt(0)
	v_mfma_f32_32x32x16_bf16 v[200:215], v[228:231], v[248:251], v[200:215]
	v_add_f32_e32 v243, v152, v243
	v_add_f32_e32 v243, v153, v243
	v_add_f32_e32 v243, v154, v243
	v_add_f32_e32 v243, v155, v243
	v_add_f32_e32 v243, v156, v243
	v_add_f32_e32 v243, v157, v243
	v_add_f32_e32 v243, v158, v243
	v_add_f32_e32 v243, v159, v243
	v_add_f32_e32 v196, v196, v243
	v_cvt_pk_bf16_f32 v144, v144, v145
	v_cvt_pk_bf16_f32 v145, v146, v147
	v_cvt_pk_bf16_f32 v146, v148, v149
	v_cvt_pk_bf16_f32 v147, v150, v151
	v_cvt_pk_bf16_f32 v148, v152, v153
	v_cvt_pk_bf16_f32 v149, v154, v155
	v_cvt_pk_bf16_f32 v150, v156, v157
	v_cvt_pk_bf16_f32 v151, v158, v159
	ds_read_b128 v[216:219], v198 offset:0
	ds_read_b128 v[220:223], v198 offset:32
	ds_read_b128 v[224:227], v198 offset:4608
	ds_read_b128 v[228:231], v198 offset:4640
	ds_read_b128 v[232:235], v198 offset:9216
	ds_read_b128 v[236:239], v198 offset:9248
	ds_read_b128 v[244:247], v198 offset:13824
	ds_read_b128 v[248:251], v198 offset:13856
	v_exp_f32_e32 v200, v200
	v_exp_f32_e32 v201, v201
	v_exp_f32_e32 v202, v202
	v_exp_f32_e32 v203, v203
	v_exp_f32_e32 v204, v204
	v_exp_f32_e32 v205, v205
	v_exp_f32_e32 v206, v206
	v_exp_f32_e32 v207, v207
	v_exp_f32_e32 v208, v208
	v_exp_f32_e32 v209, v209
	v_exp_f32_e32 v210, v210
	v_exp_f32_e32 v211, v211
	v_exp_f32_e32 v212, v212
	v_exp_f32_e32 v213, v213
	v_exp_f32_e32 v214, v214
	v_exp_f32_e32 v215, v215
	v_add_f32_e32 v243, v200, v201
	v_add_f32_e32 v243, v202, v243
	v_add_f32_e32 v243, v203, v243
	v_add_f32_e32 v243, v204, v243
	v_add_f32_e32 v243, v205, v243
	v_add_f32_e32 v243, v206, v243
	v_add_f32_e32 v243, v207, v243
	v_add_f32_e32 v243, v208, v243
	v_add_f32_e32 v243, v209, v243
	v_add_f32_e32 v243, v210, v243
	v_add_f32_e32 v243, v211, v243
	v_add_f32_e32 v243, v212, v243
	v_add_f32_e32 v243, v213, v243
	v_add_f32_e32 v243, v214, v243
	v_add_f32_e32 v243, v215, v243
	v_add_f32_e32 v197, v197, v243
	v_cvt_pk_bf16_f32 v200, v200, v201
	v_cvt_pk_bf16_f32 v201, v202, v203
	v_cvt_pk_bf16_f32 v202, v204, v205
	v_cvt_pk_bf16_f32 v203, v206, v207
	v_cvt_pk_bf16_f32 v204, v208, v209
	v_cvt_pk_bf16_f32 v205, v210, v211
	v_cvt_pk_bf16_f32 v206, v212, v213
	v_cvt_pk_bf16_f32 v207, v214, v215
	s_waitcnt lgkmcnt(7)
	v_mfma_f32_32x32x16_bf16 v[112:127], v[216:219], v[144:147], v[112:127]
	v_mfma_f32_32x32x16_bf16 v[128:143], v[216:219], v[200:203], v[128:143]
	s_waitcnt lgkmcnt(5)
	v_mfma_f32_32x32x16_bf16 v[80:95], v[224:227], v[144:147], v[80:95]
	v_mfma_f32_32x32x16_bf16 v[96:111], v[224:227], v[200:203], v[96:111]
	s_waitcnt lgkmcnt(3)
	v_mfma_f32_32x32x16_bf16 v[48:63], v[232:235], v[144:147], v[48:63]
	v_mfma_f32_32x32x16_bf16 v[64:79], v[232:235], v[200:203], v[64:79]
	s_waitcnt lgkmcnt(1)
	v_mfma_f32_32x32x16_bf16 v[16:31], v[244:247], v[144:147], v[16:31]
	v_mfma_f32_32x32x16_bf16 v[32:47], v[244:247], v[200:203], v[32:47]
	s_waitcnt lgkmcnt(0)
	v_mfma_f32_32x32x16_bf16 v[112:127], v[220:223], v[148:151], v[112:127]
	v_mfma_f32_32x32x16_bf16 v[128:143], v[220:223], v[204:207], v[128:143]
	v_mfma_f32_32x32x16_bf16 v[80:95], v[228:231], v[148:151], v[80:95]
	v_mfma_f32_32x32x16_bf16 v[96:111], v[228:231], v[204:207], v[96:111]
	v_mfma_f32_32x32x16_bf16 v[48:63], v[236:239], v[148:151], v[48:63]
	v_mfma_f32_32x32x16_bf16 v[64:79], v[236:239], v[204:207], v[64:79]
	s_waitcnt lgkmcnt(0)
	v_mfma_f32_32x32x16_bf16 v[16:31], v[248:251], v[148:151], v[16:31]
	v_mfma_f32_32x32x16_bf16 v[32:47], v[248:251], v[204:207], v[32:47]
	ds_read_b128 v[216:219], v199 offset:4608
	ds_read_b128 v[232:235], v193 offset:0
	ds_read_b128 v[220:223], v199 offset:4640
	ds_read_b128 v[236:239], v193 offset:32
	ds_read_b128 v[224:227], v199 offset:4672
	ds_read_b128 v[244:247], v193 offset:64
	ds_read_b128 v[228:231], v199 offset:4704
	ds_read_b128 v[248:251], v193 offset:96
	s_waitcnt lgkmcnt(6)
	v_mfma_f32_32x32x16_bf16 v[144:159], v[216:219], v[232:235], v[0:15]
	s_waitcnt lgkmcnt(4)
	v_mfma_f32_32x32x16_bf16 v[144:159], v[220:223], v[236:239], v[144:159]
	s_waitcnt lgkmcnt(2)
	v_mfma_f32_32x32x16_bf16 v[144:159], v[224:227], v[244:247], v[144:159]
	s_waitcnt lgkmcnt(0)
	v_mfma_f32_32x32x16_bf16 v[144:159], v[228:231], v[248:251], v[144:159]
	ds_read_b128 v[216:219], v199 offset:13824
	ds_read_b128 v[232:235], v193 offset:36864
	ds_read_b128 v[220:223], v199 offset:13856
	ds_read_b128 v[236:239], v193 offset:36896
	ds_read_b128 v[224:227], v199 offset:13888
	ds_read_b128 v[244:247], v193 offset:36928
	ds_read_b128 v[228:231], v199 offset:13920
	ds_read_b128 v[248:251], v193 offset:36960
	s_nop 3
	v_exp_f32_e32 v144, v144
	v_exp_f32_e32 v145, v145
	v_exp_f32_e32 v146, v146
	v_exp_f32_e32 v147, v147
	v_exp_f32_e32 v148, v148
	v_exp_f32_e32 v149, v149
	v_exp_f32_e32 v150, v150
	v_exp_f32_e32 v151, v151
	v_exp_f32_e32 v152, v152
	v_exp_f32_e32 v153, v153
	v_exp_f32_e32 v154, v154
	v_exp_f32_e32 v155, v155
	v_exp_f32_e32 v156, v156
	v_exp_f32_e32 v157, v157
	v_exp_f32_e32 v158, v158
	v_exp_f32_e32 v159, v159
	v_add_f32_e32 v243, v144, v145
	v_add_f32_e32 v243, v146, v243
	v_add_f32_e32 v243, v147, v243
	v_add_f32_e32 v243, v148, v243
	v_add_f32_e32 v243, v149, v243
	v_add_f32_e32 v243, v150, v243
	v_add_f32_e32 v243, v151, v243
	s_waitcnt lgkmcnt(6)
	v_mfma_f32_32x32x16_bf16 v[200:215], v[216:219], v[232:235], v[0:15]
	s_waitcnt lgkmcnt(4)
	v_mfma_f32_32x32x16_bf16 v[200:215], v[220:223], v[236:239], v[200:215]
	s_waitcnt lgkmcnt(2)
	v_mfma_f32_32x32x16_bf16 v[200:215], v[224:227], v[244:247], v[200:215]
	s_waitcnt lgkmcnt(0)
	v_mfma_f32_32x32x16_bf16 v[200:215], v[228:231], v[248:251], v[200:215]
	v_add_f32_e32 v243, v152, v243
	v_add_f32_e32 v243, v153, v243
	v_add_f32_e32 v243, v154, v243
	v_add_f32_e32 v243, v155, v243
	v_add_f32_e32 v243, v156, v243
	v_add_f32_e32 v243, v157, v243
	v_add_f32_e32 v243, v158, v243
	v_add_f32_e32 v243, v159, v243
	v_add_f32_e32 v196, v196, v243
	v_cvt_pk_bf16_f32 v144, v144, v145
	v_cvt_pk_bf16_f32 v145, v146, v147
	v_cvt_pk_bf16_f32 v146, v148, v149
	v_cvt_pk_bf16_f32 v147, v150, v151
	v_cvt_pk_bf16_f32 v148, v152, v153
	v_cvt_pk_bf16_f32 v149, v154, v155
	v_cvt_pk_bf16_f32 v150, v156, v157
	v_cvt_pk_bf16_f32 v151, v158, v159
	ds_read_b128 v[216:219], v198 offset:64
	ds_read_b128 v[220:223], v198 offset:96
	ds_read_b128 v[224:227], v198 offset:4672
	ds_read_b128 v[228:231], v198 offset:4704
	ds_read_b128 v[232:235], v198 offset:9280
	ds_read_b128 v[236:239], v198 offset:9312
	ds_read_b128 v[244:247], v198 offset:13888
	ds_read_b128 v[248:251], v198 offset:13920
	v_exp_f32_e32 v200, v200
	v_exp_f32_e32 v201, v201
	v_exp_f32_e32 v202, v202
	v_exp_f32_e32 v203, v203
	v_exp_f32_e32 v204, v204
	v_exp_f32_e32 v205, v205
	v_exp_f32_e32 v206, v206
	v_exp_f32_e32 v207, v207
	v_exp_f32_e32 v208, v208
	v_exp_f32_e32 v209, v209
	v_exp_f32_e32 v210, v210
	v_exp_f32_e32 v211, v211
	v_exp_f32_e32 v212, v212
	v_exp_f32_e32 v213, v213
	v_exp_f32_e32 v214, v214
	v_exp_f32_e32 v215, v215
	v_add_f32_e32 v243, v200, v201
	v_add_f32_e32 v243, v202, v243
	v_add_f32_e32 v243, v203, v243
	v_add_f32_e32 v243, v204, v243
	v_add_f32_e32 v243, v205, v243
	v_add_f32_e32 v243, v206, v243
	v_add_f32_e32 v243, v207, v243
	v_add_f32_e32 v243, v208, v243
	v_add_f32_e32 v243, v209, v243
	v_add_f32_e32 v243, v210, v243
	v_add_f32_e32 v243, v211, v243
	v_add_f32_e32 v243, v212, v243
	v_add_f32_e32 v243, v213, v243
	v_add_f32_e32 v243, v214, v243
	v_add_f32_e32 v243, v215, v243
	v_add_f32_e32 v197, v197, v243
	v_cvt_pk_bf16_f32 v200, v200, v201
	v_cvt_pk_bf16_f32 v201, v202, v203
	v_cvt_pk_bf16_f32 v202, v204, v205
	v_cvt_pk_bf16_f32 v203, v206, v207
	v_cvt_pk_bf16_f32 v204, v208, v209
	v_cvt_pk_bf16_f32 v205, v210, v211
	v_cvt_pk_bf16_f32 v206, v212, v213
	v_cvt_pk_bf16_f32 v207, v214, v215
	s_add_i32 s4, s42, 1
	s_cmp_lt_u32 s4, s98
	s_cbranch_scc1 .LBB0_111
	s_waitcnt lgkmcnt(7)
	v_mfma_f32_32x32x16_bf16 v[112:127], v[216:219], v[144:147], v[112:127]
	v_mfma_f32_32x32x16_bf16 v[128:143], v[216:219], v[200:203], v[128:143]
	s_waitcnt lgkmcnt(5)
	v_mfma_f32_32x32x16_bf16 v[80:95], v[224:227], v[144:147], v[80:95]
	v_mfma_f32_32x32x16_bf16 v[96:111], v[224:227], v[200:203], v[96:111]
	s_waitcnt lgkmcnt(3)
	v_mfma_f32_32x32x16_bf16 v[48:63], v[232:235], v[144:147], v[48:63]
	v_mfma_f32_32x32x16_bf16 v[64:79], v[232:235], v[200:203], v[64:79]
	s_waitcnt lgkmcnt(1)
	v_mfma_f32_32x32x16_bf16 v[16:31], v[244:247], v[144:147], v[16:31]
	v_mfma_f32_32x32x16_bf16 v[32:47], v[244:247], v[200:203], v[32:47]
	s_waitcnt lgkmcnt(0)
	v_mfma_f32_32x32x16_bf16 v[112:127], v[220:223], v[148:151], v[112:127]
	v_mfma_f32_32x32x16_bf16 v[128:143], v[220:223], v[204:207], v[128:143]
	v_mfma_f32_32x32x16_bf16 v[80:95], v[228:231], v[148:151], v[80:95]
	v_mfma_f32_32x32x16_bf16 v[96:111], v[228:231], v[204:207], v[96:111]
	v_mfma_f32_32x32x16_bf16 v[48:63], v[236:239], v[148:151], v[48:63]
	v_mfma_f32_32x32x16_bf16 v[64:79], v[236:239], v[204:207], v[64:79]
	s_waitcnt lgkmcnt(0)
	v_mfma_f32_32x32x16_bf16 v[16:31], v[248:251], v[148:151], v[16:31]
	v_mfma_f32_32x32x16_bf16 v[32:47], v[248:251], v[204:207], v[32:47]
	s_branch .LBB0_111

.LBB0_119:
	v_add_u32_e32 v252, 0x9000, v190
	s_waitcnt vmcnt(3)
	ds_write_b128 v189, v[160:163] offset:36864
	s_waitcnt vmcnt(1)
	ds_write2_b64 v252, v[164:165], v[166:167] offset1:2
	ds_write_b128 v189, v[168:171] offset:46080
	v_add_u32_e32 v252, 0xb000, v190
	s_waitcnt vmcnt(0)
	ds_write2_b64 v252, v[172:173], v[174:175] offset0:128 offset1:130
	s_add_i32 s42, s42, 2
	s_cmp_ge_u32 s42, s99
	s_cbranch_scc0 .LBB0_115
	s_branch .LBB0_116
